# norm phases: the 512 sample rows (with their split-K fold) are spread one per 4th wave over all workgroups instead of piling a fifth trip onto the first 64 workgroups
# baseline (speedup 1.0000x reference)
; __device__ __forceinline__ void phase_norm(PP P, int l, int which, int nsl, const float* fgate, float fscale, const Ids I) {
;     ...
;     for (int row0 = gw; row0 < MT; row0 += 2 * nw) {
;         const int rows[2] = {row0, (row0 + nw < MT) ? row0 + nw : row0};
;         f32x4 v[2][4]; float ss[2];
; #pragma unroll
;         for (int j = 0; j < 2; ++j) { const int row = rows[j];
;             const float* xr = from_in ? (row < MTP ? P->in[I_XP] + (size_t)row * D : P->in[I_XS] + (size_t)(row - MTP) * D) : xb + (size_t)row * D;
; #pragma unroll
;             for (int i = 0; i < 4; ++i) v[j][i] = *(const f32x4*)(xr + lane * 4 + 256 * i);
;             if (nsl > 0 && row >= MTP && !(j == 1 && row == row0)) {
.LBB0_539:
	s_add_i32 s8, s8, s2
	s_add_i32 s16, s16, s2
	s_cmpk_lt_i32 s8, 0x4000
	s_cbranch_scc1 .LBB0_540
	s_cmpk_gt_i32 s8, 0x47ff
	s_cbranch_scc1 .LBB0_591
	s_and_b32 s9, s16, 3
	s_cmp_lg_u32 s9, 0
	s_cbranch_scc1 .LBB0_591
	s_lshr_b32 s16, s16, 2
	s_add_i32 s8, s16, 0x4000
